# gate/up tile loop: next-tile index decode by shifts/masks instead of the generic division chain
# baseline (speedup 1.0000x reference)
.LBB0_789:
	s_add_i32 s74, s74, 1
	s_mul_i32 s6, s74, s3
	s_mul_hi_u32 s7, s74, s34
	s_add_i32 s7, s7, s6
	s_mul_i32 s6, s74, s34
	s_add_u32 s22, s6, s0
	s_addc_u32 s23, s7, s73
	v_mov_b64_e32 v[0:1], 0x57f
	v_cmp_gt_i64_e64 s[6:7], s[22:23], v[0:1]
	s_and_b64 vcc, exec, s[6:7]
	s_cbranch_vccnz .LBB0_791
	s_and_b32 s9, s22, 7
	s_lshl_b32 s19, s9, 3
	s_bfe_u32 s9, s22, 0x30003
	s_or_b32 s20, s19, s9
	s_lshr_b32 s18, s22, 6
